# v134 + sigmoid in-proj epilogue: next row's RMSNorm partial-sum loads issued one row ahead, counted vmcnt(2)
# baseline (speedup 1.0000x reference)
.LBB0_174:
	s_cmp_gt_i32 s16, 7
	s_mov_b64 s[42:43], -1
	s_cbranch_scc0 .LBB0_196
	s_add_i32 s17, s16, -12
	s_cmp_gt_u32 s17, 15
	s_cbranch_scc0 .LBB0_177
	v_ashrrev_i32_e32 v171, 31, v170
	v_lshlrev_b64 v[134:135], 6, v[170:171]
	v_lshl_add_u64 v[146:147], s[92:93], 0, v[134:135]
	global_load_dwordx4 v[134:137], v[146:147], off offset:32
	global_load_dwordx4 v[138:141], v[146:147], off offset:48
	global_load_dwordx4 v[142:145], v[146:147], off
	s_nop 0
	global_load_dwordx4 v[146:149], v[146:147], off offset:16
	s_cmp_lt_u32 s16, 12
	s_cselect_b64 vcc, -1, 0
	s_cmp_lt_u32 s16, 32
	s_mov_b32 s17, 0x18c00000
	s_cselect_b32 s17, s17, 0x1ac00000
	s_and_b64 s[42:43], vcc, exec
	s_cselect_b32 s17, 0x12c00000, s17
	s_add_u32 s42, s38, s17
	s_addc_u32 s43, s39, 0
	s_add_i32 s17, s16, -8
	s_and_b32 s22, s16, 3
	s_and_b64 s[46:47], vcc, exec
	s_cselect_b32 s17, s17, s22
	v_lshlrev_b32_e32 v0, 1, v222
	v_lshl_or_b32 v0, s17, 9, v0
	v_lshl_add_u64 v[130:131], s[42:43], 0, v[0:1]
	v_lshlrev_b64 v[132:133], 11, v[170:171]
	v_lshl_add_u64 v[132:133], v[130:131], 0, v[132:133]
	s_mov_b64 s[42:43], 0
	s_waitcnt vmcnt(0)
	v_pk_add_f32 v[136:137], v[136:137], v[140:141]
	v_pk_add_f32 v[134:135], v[134:135], v[138:139]
	v_pk_add_f32 v[144:145], v[144:145], v[148:149]
	v_pk_add_f32 v[142:143], v[142:143], v[146:147]
	v_pk_add_f32 v[136:137], v[144:145], v[136:137]
	v_pk_add_f32 v[134:135], v[142:143], v[134:135]
	s_nop 0
	v_pk_mov_b32 v[138:139], v[134:135], v[136:137] op_sel:[1,0]
	v_mov_b32_e32 v135, v137
	v_pk_add_f32 v[134:135], v[138:139], v[134:135]
	s_nop 0
	v_add_f32_e32 v0, v134, v135
	v_fmamk_f32 v0, v0, 0x3a800000, v211
	v_rsq_f32_e32 v0, v0
	s_nop 0
	v_or_b32_e32 v186, 16, v170
	v_ashrrev_i32_e32 v187, 31, v186
	v_lshlrev_b64 v[188:189], 6, v[186:187]
	v_lshl_add_u64 v[188:189], s[92:93], 0, v[188:189]
	global_load_dwordx4 v[190:193], v[188:189], off offset:32
	global_load_dwordx4 v[194:197], v[188:189], off offset:48
	global_load_dwordx4 v[198:201], v[188:189], off
	global_load_dwordx4 v[202:205], v[188:189], off offset:16
	v_pk_mul_f32 v[136:137], v[126:127], v[0:1] op_sel_hi:[1,0]
	v_pk_mul_f32 v[140:141], v[122:123], v[0:1] op_sel_hi:[1,0]
	v_mul_f32_e32 v142, 0xbfb8aa3b, v136
	v_exp_f32_e32 v142, v142
	v_mul_f32_e32 v143, 0xbfb8aa3b, v140
	v_exp_f32_e32 v143, v143
	v_pk_mul_f32 v[134:135], v[128:129], v[0:1] op_sel_hi:[1,0]
	v_add_f32_e32 v142, 1.0, v142
	v_rcp_f32_e32 v142, v142
	v_add_f32_e32 v143, 1.0, v143
	v_rcp_f32_e32 v143, v143
	v_pk_mul_f32 v[138:139], v[124:125], v[0:1] op_sel_hi:[1,0]
	v_mul_f32_e32 v136, v136, v142
	v_cndmask_b32_e32 v136, v142, v136, vcc
	v_mul_f32_e32 v140, v140, v143
	v_mul_f32_e32 v142, 0xbfb8aa3b, v137
	v_cndmask_b32_e32 v140, v143, v140, vcc
	v_exp_f32_e32 v142, v142
	v_mul_f32_e32 v143, 0xbfb8aa3b, v141
	v_exp_f32_e32 v143, v143
	v_add_f32_e32 v142, 1.0, v142
	v_rcp_f32_e32 v142, v142
	v_add_f32_e32 v143, 1.0, v143
	v_rcp_f32_e32 v143, v143
	v_mul_f32_e32 v137, v137, v142
	v_cndmask_b32_e32 v137, v142, v137, vcc
	v_mul_f32_e32 v141, v141, v143
	v_mul_f32_e32 v142, 0xbfb8aa3b, v134
	v_cndmask_b32_e32 v141, v143, v141, vcc
	v_exp_f32_e32 v142, v142
	v_mul_f32_e32 v143, 0xbfb8aa3b, v138
	v_exp_f32_e32 v143, v143
	v_add_f32_e32 v142, 1.0, v142
	v_rcp_f32_e32 v142, v142
	v_add_f32_e32 v143, 1.0, v143
	v_rcp_f32_e32 v143, v143
	v_mul_f32_e32 v134, v134, v142
	v_cndmask_b32_e32 v142, v142, v134, vcc
	v_mul_f32_e32 v134, v138, v143
	v_cndmask_b32_e32 v138, v143, v134, vcc
	v_mul_f32_e32 v134, 0xbfb8aa3b, v135
	v_exp_f32_e32 v134, v134
	v_mul_f32_e32 v143, 0xbfb8aa3b, v139
	v_exp_f32_e32 v143, v143
	v_add_f32_e32 v134, 1.0, v134
	v_rcp_f32_e32 v134, v134
	v_add_f32_e32 v143, 1.0, v143
	v_rcp_f32_e32 v143, v143
	v_mul_f32_e32 v135, v135, v134
	v_cndmask_b32_e32 v135, v134, v135, vcc
	v_mul_f32_e32 v134, v139, v143
	v_cndmask_b32_e32 v139, v143, v134, vcc
	v_cvt_pk_bf16_f32 v134, v136, v137
	v_cvt_pk_bf16_f32 v135, v142, v135
	v_cvt_pk_bf16_f32 v136, v140, v141
	v_cvt_pk_bf16_f32 v137, v138, v139
	v_pk_mul_f32 v[138:139], v[118:119], v[0:1] op_sel_hi:[1,0]
	global_store_dwordx4 v[132:133], v[134:137], off
	v_pk_mul_f32 v[140:141], v[110:111], v[0:1] op_sel_hi:[1,0]
	s_nop 0
	v_pk_mul_f32 v[134:135], v[120:121], v[0:1] op_sel_hi:[1,0]
	v_pk_mul_f32 v[136:137], v[112:113], v[0:1] op_sel_hi:[1,0]
	v_mul_f32_e32 v0, 0xbfb8aa3b, v138
	v_exp_f32_e32 v0, v0
	v_mul_f32_e32 v142, 0xbfb8aa3b, v140
	v_exp_f32_e32 v142, v142
	v_add_f32_e32 v0, 1.0, v0
	v_rcp_f32_e32 v0, v0
	v_add_f32_e32 v142, 1.0, v142
	v_rcp_f32_e32 v142, v142
	v_mul_f32_e32 v138, v138, v0
	v_cndmask_b32_e32 v0, v0, v138, vcc
	v_mul_f32_e32 v138, v140, v142
	v_mul_f32_e32 v140, 0xbfb8aa3b, v139
	v_cndmask_b32_e32 v138, v142, v138, vcc
	v_exp_f32_e32 v140, v140
	v_mul_f32_e32 v142, 0xbfb8aa3b, v141
	v_exp_f32_e32 v142, v142
	v_add_f32_e32 v140, 1.0, v140
	v_rcp_f32_e32 v140, v140
	v_add_f32_e32 v142, 1.0, v142
	v_rcp_f32_e32 v142, v142
	v_mul_f32_e32 v139, v139, v140
	v_cndmask_b32_e32 v139, v140, v139, vcc
	v_mul_f32_e32 v140, v141, v142
	v_mul_f32_e32 v141, 0xbfb8aa3b, v134
	v_cndmask_b32_e32 v140, v142, v140, vcc
	v_exp_f32_e32 v141, v141
	v_mul_f32_e32 v142, 0xbfb8aa3b, v136
	v_exp_f32_e32 v142, v142
	v_add_f32_e32 v141, 1.0, v141
	v_rcp_f32_e32 v141, v141
	v_add_f32_e32 v142, 1.0, v142
	v_rcp_f32_e32 v142, v142
	v_mul_f32_e32 v134, v134, v141
	v_cndmask_b32_e32 v141, v141, v134, vcc
	v_mul_f32_e32 v134, v136, v142
	v_cndmask_b32_e32 v142, v142, v134, vcc
	v_mul_f32_e32 v134, 0xbfb8aa3b, v135
	v_exp_f32_e32 v134, v134
	v_mul_f32_e32 v136, 0xbfb8aa3b, v137
	v_exp_f32_e32 v136, v136
	v_add_f32_e32 v134, 1.0, v134
	v_rcp_f32_e32 v134, v134
	v_add_f32_e32 v136, 1.0, v136
	v_rcp_f32_e32 v136, v136
	v_mul_f32_e32 v135, v135, v134
	v_cndmask_b32_e32 v135, v134, v135, vcc
	v_mul_f32_e32 v134, v137, v136
	v_cndmask_b32_e32 v137, v136, v134, vcc
	v_cvt_pk_bf16_f32 v134, v0, v139
	v_cvt_pk_bf16_f32 v135, v141, v135
	v_cvt_pk_bf16_f32 v136, v138, v140
	v_cvt_pk_bf16_f32 v137, v142, v137
	global_store_dwordx4 v[132:133], v[134:137], off offset:64
	s_nop 1
	v_or_b32_e32 v134, 16, v170
	v_ashrrev_i32_e32 v135, 31, v134
	v_lshlrev_b64 v[132:133], 11, v[134:135]
	v_lshl_add_u64 v[132:133], v[130:131], 0, v[132:133]
	s_waitcnt vmcnt(2)
	v_pk_add_f32 v[136:137], v[192:193], v[196:197]
	v_pk_add_f32 v[134:135], v[190:191], v[194:195]
	v_pk_add_f32 v[144:145], v[200:201], v[204:205]
	v_pk_add_f32 v[142:143], v[198:199], v[202:203]
	v_pk_add_f32 v[136:137], v[144:145], v[136:137]
	v_pk_add_f32 v[134:135], v[142:143], v[134:135]
	s_nop 0
	v_pk_mov_b32 v[138:139], v[134:135], v[136:137] op_sel:[1,0]
	v_mov_b32_e32 v135, v137
	v_pk_add_f32 v[134:135], v[138:139], v[134:135]
	s_nop 0
	v_add_f32_e32 v0, v134, v135
	v_fmamk_f32 v0, v0, 0x3a800000, v211
	v_rsq_f32_e32 v0, v0
	s_nop 0
	v_or_b32_e32 v186, 32, v170
	v_ashrrev_i32_e32 v187, 31, v186
	v_lshlrev_b64 v[188:189], 6, v[186:187]
	v_lshl_add_u64 v[188:189], s[92:93], 0, v[188:189]
	global_load_dwordx4 v[190:193], v[188:189], off offset:32
	global_load_dwordx4 v[194:197], v[188:189], off offset:48
	global_load_dwordx4 v[198:201], v[188:189], off
	global_load_dwordx4 v[202:205], v[188:189], off offset:16
	v_pk_mul_f32 v[138:139], v[114:115], v[0:1] op_sel_hi:[1,0]
	v_pk_mul_f32 v[140:141], v[106:107], v[0:1] op_sel_hi:[1,0]
	v_mul_f32_e32 v142, 0xbfb8aa3b, v138
	v_exp_f32_e32 v142, v142
	v_mul_f32_e32 v143, 0xbfb8aa3b, v140
	v_exp_f32_e32 v143, v143
	v_pk_mul_f32 v[134:135], v[116:117], v[0:1] op_sel_hi:[1,0]
	v_add_f32_e32 v142, 1.0, v142
	v_rcp_f32_e32 v142, v142
	v_add_f32_e32 v143, 1.0, v143
	v_rcp_f32_e32 v143, v143
	v_pk_mul_f32 v[136:137], v[108:109], v[0:1] op_sel_hi:[1,0]
	v_mul_f32_e32 v138, v138, v142
	v_cndmask_b32_e32 v138, v142, v138, vcc
	v_mul_f32_e32 v140, v140, v143
	v_mul_f32_e32 v142, 0xbfb8aa3b, v139
	v_cndmask_b32_e32 v140, v143, v140, vcc
	v_exp_f32_e32 v142, v142
	v_mul_f32_e32 v143, 0xbfb8aa3b, v141
	v_exp_f32_e32 v143, v143
	v_add_f32_e32 v142, 1.0, v142
	v_rcp_f32_e32 v142, v142
	v_add_f32_e32 v143, 1.0, v143
	v_rcp_f32_e32 v143, v143
	v_mul_f32_e32 v139, v139, v142
	v_cndmask_b32_e32 v139, v142, v139, vcc
	v_mul_f32_e32 v141, v141, v143
	v_mul_f32_e32 v142, 0xbfb8aa3b, v134
	v_cndmask_b32_e32 v141, v143, v141, vcc
	v_exp_f32_e32 v142, v142
	v_mul_f32_e32 v143, 0xbfb8aa3b, v136
	v_exp_f32_e32 v143, v143
	v_add_f32_e32 v142, 1.0, v142
	v_rcp_f32_e32 v142, v142
	v_add_f32_e32 v143, 1.0, v143
	v_rcp_f32_e32 v143, v143
	v_mul_f32_e32 v134, v134, v142
	v_cndmask_b32_e32 v142, v142, v134, vcc
	v_mul_f32_e32 v134, v136, v143
	v_cndmask_b32_e32 v143, v143, v134, vcc
	v_mul_f32_e32 v134, 0xbfb8aa3b, v135
	v_exp_f32_e32 v134, v134
	v_mul_f32_e32 v136, 0xbfb8aa3b, v137
	v_exp_f32_e32 v136, v136
	v_add_f32_e32 v134, 1.0, v134
	v_rcp_f32_e32 v134, v134
	v_add_f32_e32 v136, 1.0, v136
	v_rcp_f32_e32 v136, v136
	v_mul_f32_e32 v135, v135, v134
	v_cndmask_b32_e32 v135, v134, v135, vcc
	v_mul_f32_e32 v134, v137, v136
	v_cndmask_b32_e32 v137, v136, v134, vcc
	v_cvt_pk_bf16_f32 v134, v138, v139
	v_cvt_pk_bf16_f32 v135, v142, v135
	v_cvt_pk_bf16_f32 v136, v140, v141
	v_cvt_pk_bf16_f32 v137, v143, v137
	global_store_dwordx4 v[132:133], v[134:137], off
	v_pk_mul_f32 v[138:139], v[96:97], v[0:1] op_sel_hi:[1,0]
	v_pk_mul_f32 v[140:141], v[94:95], v[0:1] op_sel_hi:[1,0]
	v_pk_mul_f32 v[136:137], v[102:103], v[0:1] op_sel_hi:[1,0]
	v_pk_mul_f32 v[134:135], v[104:105], v[0:1] op_sel_hi:[1,0]
	v_mul_f32_e32 v0, 0xbfb8aa3b, v136
	v_exp_f32_e32 v0, v0
	v_mul_f32_e32 v142, 0xbfb8aa3b, v140
	v_exp_f32_e32 v142, v142
	v_add_f32_e32 v0, 1.0, v0
	v_rcp_f32_e32 v0, v0
	v_add_f32_e32 v142, 1.0, v142
	v_rcp_f32_e32 v142, v142
	v_mul_f32_e32 v136, v136, v0
	v_cndmask_b32_e32 v0, v0, v136, vcc
	v_mul_f32_e32 v136, v140, v142
	v_mul_f32_e32 v140, 0xbfb8aa3b, v137
	v_cndmask_b32_e32 v136, v142, v136, vcc
	v_exp_f32_e32 v140, v140
	v_mul_f32_e32 v142, 0xbfb8aa3b, v141
	v_exp_f32_e32 v142, v142
	v_add_f32_e32 v140, 1.0, v140
	v_rcp_f32_e32 v140, v140
	v_add_f32_e32 v142, 1.0, v142
	v_rcp_f32_e32 v142, v142
	v_mul_f32_e32 v137, v137, v140
	v_cndmask_b32_e32 v137, v140, v137, vcc
	v_mul_f32_e32 v140, v141, v142
	v_mul_f32_e32 v141, 0xbfb8aa3b, v134
	v_cndmask_b32_e32 v140, v142, v140, vcc
	v_exp_f32_e32 v141, v141
	v_mul_f32_e32 v142, 0xbfb8aa3b, v138
	v_exp_f32_e32 v142, v142
	v_add_f32_e32 v141, 1.0, v141
	v_rcp_f32_e32 v141, v141
	v_add_f32_e32 v142, 1.0, v142
	v_rcp_f32_e32 v142, v142
	v_mul_f32_e32 v134, v134, v141
	v_cndmask_b32_e32 v141, v141, v134, vcc
	v_mul_f32_e32 v134, v138, v142
	v_cndmask_b32_e32 v138, v142, v134, vcc
	v_mul_f32_e32 v134, 0xbfb8aa3b, v135
	v_exp_f32_e32 v134, v134
	v_mul_f32_e32 v142, 0xbfb8aa3b, v139
	v_exp_f32_e32 v142, v142
	v_add_f32_e32 v134, 1.0, v134
	v_rcp_f32_e32 v134, v134
	v_add_f32_e32 v142, 1.0, v142
	v_rcp_f32_e32 v142, v142
	v_mul_f32_e32 v135, v135, v134
	v_cndmask_b32_e32 v135, v134, v135, vcc
	v_mul_f32_e32 v134, v139, v142
	v_cndmask_b32_e32 v139, v142, v134, vcc
	v_cvt_pk_bf16_f32 v134, v0, v137
	v_cvt_pk_bf16_f32 v135, v141, v135
	v_cvt_pk_bf16_f32 v136, v136, v140
	v_cvt_pk_bf16_f32 v137, v138, v139
	global_store_dwordx4 v[132:133], v[134:137], off offset:64
	s_nop 1
	v_or_b32_e32 v134, 32, v170
	v_ashrrev_i32_e32 v135, 31, v134
	v_lshlrev_b64 v[132:133], 11, v[134:135]
	v_lshl_add_u64 v[132:133], v[130:131], 0, v[132:133]
	s_waitcnt vmcnt(2)
	v_pk_add_f32 v[136:137], v[192:193], v[196:197]
	v_pk_add_f32 v[134:135], v[190:191], v[194:195]
	v_pk_add_f32 v[144:145], v[200:201], v[204:205]
	v_pk_add_f32 v[142:143], v[198:199], v[202:203]
	v_pk_add_f32 v[136:137], v[144:145], v[136:137]
	v_pk_add_f32 v[134:135], v[142:143], v[134:135]
	s_nop 0
	v_pk_mov_b32 v[138:139], v[134:135], v[136:137] op_sel:[1,0]
	v_mov_b32_e32 v135, v137
	v_pk_add_f32 v[134:135], v[138:139], v[134:135]
	s_nop 0
	v_add_f32_e32 v0, v134, v135
	v_fmamk_f32 v0, v0, 0x3a800000, v211
	v_rsq_f32_e32 v0, v0
	s_nop 0
	v_or_b32_e32 v186, 48, v170
	v_ashrrev_i32_e32 v187, 31, v186
	v_lshlrev_b64 v[188:189], 6, v[186:187]
	v_lshl_add_u64 v[188:189], s[92:93], 0, v[188:189]
	global_load_dwordx4 v[190:193], v[188:189], off offset:32
	global_load_dwordx4 v[194:197], v[188:189], off offset:48
	global_load_dwordx4 v[198:201], v[188:189], off
	global_load_dwordx4 v[202:205], v[188:189], off offset:16
	v_pk_mul_f32 v[136:137], v[98:99], v[0:1] op_sel_hi:[1,0]
	v_pk_mul_f32 v[140:141], v[90:91], v[0:1] op_sel_hi:[1,0]
	v_mul_f32_e32 v142, 0xbfb8aa3b, v136
	v_exp_f32_e32 v142, v142
	v_mul_f32_e32 v143, 0xbfb8aa3b, v140
	v_exp_f32_e32 v143, v143
	v_pk_mul_f32 v[134:135], v[100:101], v[0:1] op_sel_hi:[1,0]
	v_add_f32_e32 v142, 1.0, v142
	v_rcp_f32_e32 v142, v142
	v_add_f32_e32 v143, 1.0, v143
	v_rcp_f32_e32 v143, v143
	v_pk_mul_f32 v[138:139], v[92:93], v[0:1] op_sel_hi:[1,0]
	v_mul_f32_e32 v136, v136, v142
	v_cndmask_b32_e32 v136, v142, v136, vcc
	v_mul_f32_e32 v140, v140, v143
	v_mul_f32_e32 v142, 0xbfb8aa3b, v137
	v_cndmask_b32_e32 v140, v143, v140, vcc
	v_exp_f32_e32 v142, v142
	v_mul_f32_e32 v143, 0xbfb8aa3b, v141
	v_exp_f32_e32 v143, v143
	v_add_f32_e32 v142, 1.0, v142
	v_rcp_f32_e32 v142, v142
	v_add_f32_e32 v143, 1.0, v143
	v_rcp_f32_e32 v143, v143
	v_mul_f32_e32 v137, v137, v142
	v_cndmask_b32_e32 v137, v142, v137, vcc
	v_mul_f32_e32 v141, v141, v143
	v_mul_f32_e32 v142, 0xbfb8aa3b, v134
	v_cndmask_b32_e32 v141, v143, v141, vcc
	v_exp_f32_e32 v142, v142
	v_mul_f32_e32 v143, 0xbfb8aa3b, v138
	v_exp_f32_e32 v143, v143
	v_add_f32_e32 v142, 1.0, v142
	v_rcp_f32_e32 v142, v142
	v_add_f32_e32 v143, 1.0, v143
	v_rcp_f32_e32 v143, v143
	v_mul_f32_e32 v134, v134, v142
	v_cndmask_b32_e32 v142, v142, v134, vcc
	v_mul_f32_e32 v134, v138, v143
	v_cndmask_b32_e32 v138, v143, v134, vcc
	v_mul_f32_e32 v134, 0xbfb8aa3b, v135
	v_exp_f32_e32 v134, v134
	v_mul_f32_e32 v143, 0xbfb8aa3b, v139
	v_exp_f32_e32 v143, v143
	v_add_f32_e32 v134, 1.0, v134
	v_rcp_f32_e32 v134, v134
	v_add_f32_e32 v143, 1.0, v143
	v_rcp_f32_e32 v143, v143
	v_mul_f32_e32 v135, v135, v134
	v_cndmask_b32_e32 v135, v134, v135, vcc
	v_mul_f32_e32 v134, v139, v143
	v_cndmask_b32_e32 v139, v143, v134, vcc
	v_cvt_pk_bf16_f32 v134, v136, v137
	v_cvt_pk_bf16_f32 v135, v142, v135
	v_cvt_pk_bf16_f32 v136, v140, v141
	v_cvt_pk_bf16_f32 v137, v138, v139
	global_store_dwordx4 v[132:133], v[134:137], off
	v_pk_mul_f32 v[138:139], v[80:81], v[0:1] op_sel_hi:[1,0]
	v_pk_mul_f32 v[140:141], v[78:79], v[0:1] op_sel_hi:[1,0]
	v_pk_mul_f32 v[136:137], v[86:87], v[0:1] op_sel_hi:[1,0]
	v_pk_mul_f32 v[134:135], v[88:89], v[0:1] op_sel_hi:[1,0]
	v_mul_f32_e32 v0, 0xbfb8aa3b, v136
	v_exp_f32_e32 v0, v0
	v_mul_f32_e32 v142, 0xbfb8aa3b, v140
	v_exp_f32_e32 v142, v142
	v_add_f32_e32 v0, 1.0, v0
	v_rcp_f32_e32 v0, v0
	v_add_f32_e32 v142, 1.0, v142
	v_rcp_f32_e32 v142, v142
	v_mul_f32_e32 v136, v136, v0
	v_cndmask_b32_e32 v0, v0, v136, vcc
	v_mul_f32_e32 v136, v140, v142
	v_mul_f32_e32 v140, 0xbfb8aa3b, v137
	v_cndmask_b32_e32 v136, v142, v136, vcc
	v_exp_f32_e32 v140, v140
	v_mul_f32_e32 v142, 0xbfb8aa3b, v141
	v_exp_f32_e32 v142, v142
	v_add_f32_e32 v140, 1.0, v140
	v_rcp_f32_e32 v140, v140
	v_add_f32_e32 v142, 1.0, v142
	v_rcp_f32_e32 v142, v142
	v_mul_f32_e32 v137, v137, v140
	v_cndmask_b32_e32 v137, v140, v137, vcc
	v_mul_f32_e32 v140, v141, v142
	v_mul_f32_e32 v141, 0xbfb8aa3b, v134
	v_cndmask_b32_e32 v140, v142, v140, vcc
	v_exp_f32_e32 v141, v141
	v_mul_f32_e32 v142, 0xbfb8aa3b, v138
	v_exp_f32_e32 v142, v142
	v_add_f32_e32 v141, 1.0, v141
	v_rcp_f32_e32 v141, v141
	v_add_f32_e32 v142, 1.0, v142
	v_rcp_f32_e32 v142, v142
	v_mul_f32_e32 v134, v134, v141
	v_cndmask_b32_e32 v141, v141, v134, vcc
	v_mul_f32_e32 v134, v138, v142
	v_cndmask_b32_e32 v138, v142, v134, vcc
	v_mul_f32_e32 v134, 0xbfb8aa3b, v135
	v_exp_f32_e32 v134, v134
	v_mul_f32_e32 v142, 0xbfb8aa3b, v139
	v_exp_f32_e32 v142, v142
	v_add_f32_e32 v134, 1.0, v134
	v_rcp_f32_e32 v134, v134
	v_add_f32_e32 v142, 1.0, v142
	v_rcp_f32_e32 v142, v142
	v_mul_f32_e32 v135, v135, v134
	v_cndmask_b32_e32 v135, v134, v135, vcc
	v_mul_f32_e32 v134, v139, v142
	v_cndmask_b32_e32 v139, v142, v134, vcc
	v_cvt_pk_bf16_f32 v134, v0, v137
	v_cvt_pk_bf16_f32 v135, v141, v135
	v_cvt_pk_bf16_f32 v136, v136, v140
	v_cvt_pk_bf16_f32 v137, v138, v139
	global_store_dwordx4 v[132:133], v[134:137], off offset:64
	s_nop 1
	v_or_b32_e32 v134, 48, v170
	v_ashrrev_i32_e32 v135, 31, v134
	v_lshlrev_b64 v[132:133], 11, v[134:135]
	v_lshl_add_u64 v[132:133], v[130:131], 0, v[132:133]
	s_waitcnt vmcnt(2)
	v_pk_add_f32 v[136:137], v[192:193], v[196:197]
	v_pk_add_f32 v[134:135], v[190:191], v[194:195]
	v_pk_add_f32 v[144:145], v[200:201], v[204:205]
	v_pk_add_f32 v[142:143], v[198:199], v[202:203]
	v_pk_add_f32 v[136:137], v[144:145], v[136:137]
	v_pk_add_f32 v[134:135], v[142:143], v[134:135]
	s_nop 0
	v_pk_mov_b32 v[138:139], v[134:135], v[136:137] op_sel:[1,0]
	v_mov_b32_e32 v135, v137
	v_pk_add_f32 v[134:135], v[138:139], v[134:135]
	s_nop 0
	v_add_f32_e32 v0, v134, v135
	v_fmamk_f32 v0, v0, 0x3a800000, v211
	v_rsq_f32_e32 v0, v0
	s_nop 0
	v_add_u32_e32 v186, 0x80, v170
	v_ashrrev_i32_e32 v187, 31, v186
	v_lshlrev_b64 v[188:189], 6, v[186:187]
	v_lshl_add_u64 v[188:189], s[92:93], 0, v[188:189]
	global_load_dwordx4 v[190:193], v[188:189], off offset:32
	global_load_dwordx4 v[194:197], v[188:189], off offset:48
	global_load_dwordx4 v[198:201], v[188:189], off
	global_load_dwordx4 v[202:205], v[188:189], off offset:16
	v_pk_mul_f32 v[136:137], v[82:83], v[0:1] op_sel_hi:[1,0]
	v_pk_mul_f32 v[140:141], v[74:75], v[0:1] op_sel_hi:[1,0]
	v_mul_f32_e32 v142, 0xbfb8aa3b, v136
	v_exp_f32_e32 v142, v142
	v_mul_f32_e32 v143, 0xbfb8aa3b, v140
	v_exp_f32_e32 v143, v143
	v_pk_mul_f32 v[134:135], v[84:85], v[0:1] op_sel_hi:[1,0]
	v_add_f32_e32 v142, 1.0, v142
	v_rcp_f32_e32 v142, v142
	v_add_f32_e32 v143, 1.0, v143
	v_rcp_f32_e32 v143, v143
	v_pk_mul_f32 v[138:139], v[76:77], v[0:1] op_sel_hi:[1,0]
	v_mul_f32_e32 v136, v136, v142
	v_cndmask_b32_e32 v136, v142, v136, vcc
	v_mul_f32_e32 v140, v140, v143
	v_mul_f32_e32 v142, 0xbfb8aa3b, v137
	v_cndmask_b32_e32 v140, v143, v140, vcc
	v_exp_f32_e32 v142, v142
	v_mul_f32_e32 v143, 0xbfb8aa3b, v141
	v_exp_f32_e32 v143, v143
	v_add_f32_e32 v142, 1.0, v142
	v_rcp_f32_e32 v142, v142
	v_add_f32_e32 v143, 1.0, v143
	v_rcp_f32_e32 v143, v143
	v_mul_f32_e32 v137, v137, v142
	v_cndmask_b32_e32 v137, v142, v137, vcc
	v_mul_f32_e32 v141, v141, v143
	v_mul_f32_e32 v142, 0xbfb8aa3b, v134
	v_cndmask_b32_e32 v141, v143, v141, vcc
	v_exp_f32_e32 v142, v142
	v_mul_f32_e32 v143, 0xbfb8aa3b, v138
	v_exp_f32_e32 v143, v143
	v_add_f32_e32 v142, 1.0, v142
	v_rcp_f32_e32 v142, v142
	v_add_f32_e32 v143, 1.0, v143
	v_rcp_f32_e32 v143, v143
	v_mul_f32_e32 v134, v134, v142
	v_cndmask_b32_e32 v142, v142, v134, vcc
	v_mul_f32_e32 v134, v138, v143
	v_cndmask_b32_e32 v138, v143, v134, vcc
	v_mul_f32_e32 v134, 0xbfb8aa3b, v135
	v_exp_f32_e32 v134, v134
	v_mul_f32_e32 v143, 0xbfb8aa3b, v139
	v_exp_f32_e32 v143, v143
	v_add_f32_e32 v134, 1.0, v134
	v_rcp_f32_e32 v134, v134
	v_add_f32_e32 v143, 1.0, v143
	v_rcp_f32_e32 v143, v143
	v_mul_f32_e32 v135, v135, v134
	v_cndmask_b32_e32 v135, v134, v135, vcc
	v_mul_f32_e32 v134, v139, v143
	v_cndmask_b32_e32 v139, v143, v134, vcc
	v_cvt_pk_bf16_f32 v134, v136, v137
	v_cvt_pk_bf16_f32 v135, v142, v135
	v_cvt_pk_bf16_f32 v136, v140, v141
	v_cvt_pk_bf16_f32 v137, v138, v139
	global_store_dwordx4 v[132:133], v[134:137], off
	v_pk_mul_f32 v[138:139], v[68:69], v[0:1] op_sel_hi:[1,0]
	v_pk_mul_f32 v[140:141], v[66:67], v[0:1] op_sel_hi:[1,0]
	v_pk_mul_f32 v[136:137], v[70:71], v[0:1] op_sel_hi:[1,0]
	v_pk_mul_f32 v[134:135], v[72:73], v[0:1] op_sel_hi:[1,0]
	v_mul_f32_e32 v0, 0xbfb8aa3b, v136
	v_exp_f32_e32 v0, v0
	v_mul_f32_e32 v142, 0xbfb8aa3b, v140
	v_exp_f32_e32 v142, v142
	v_add_f32_e32 v0, 1.0, v0
	v_rcp_f32_e32 v0, v0
	v_add_f32_e32 v142, 1.0, v142
	v_rcp_f32_e32 v142, v142
	v_mul_f32_e32 v136, v136, v0
	v_cndmask_b32_e32 v0, v0, v136, vcc
	v_mul_f32_e32 v136, v140, v142
	v_mul_f32_e32 v140, 0xbfb8aa3b, v137
	v_cndmask_b32_e32 v136, v142, v136, vcc
	v_exp_f32_e32 v140, v140
	v_mul_f32_e32 v142, 0xbfb8aa3b, v141
	v_exp_f32_e32 v142, v142
	v_add_f32_e32 v140, 1.0, v140
	v_rcp_f32_e32 v140, v140
	v_add_f32_e32 v142, 1.0, v142
	v_rcp_f32_e32 v142, v142
	v_mul_f32_e32 v137, v137, v140
	v_cndmask_b32_e32 v137, v140, v137, vcc
	v_mul_f32_e32 v140, v141, v142
	v_mul_f32_e32 v141, 0xbfb8aa3b, v134
	v_cndmask_b32_e32 v140, v142, v140, vcc
	v_exp_f32_e32 v141, v141
	v_mul_f32_e32 v142, 0xbfb8aa3b, v138
	v_exp_f32_e32 v142, v142
	v_add_f32_e32 v141, 1.0, v141
	v_rcp_f32_e32 v141, v141
	v_add_f32_e32 v142, 1.0, v142
	v_rcp_f32_e32 v142, v142
	v_mul_f32_e32 v134, v134, v141
	v_cndmask_b32_e32 v141, v141, v134, vcc
	v_mul_f32_e32 v134, v138, v142
	v_cndmask_b32_e32 v138, v142, v134, vcc
	v_mul_f32_e32 v134, 0xbfb8aa3b, v135
	v_exp_f32_e32 v134, v134
	v_mul_f32_e32 v142, 0xbfb8aa3b, v139
	v_exp_f32_e32 v142, v142
	v_add_f32_e32 v134, 1.0, v134
	v_rcp_f32_e32 v134, v134
	v_add_f32_e32 v142, 1.0, v142
	v_rcp_f32_e32 v142, v142
	v_mul_f32_e32 v135, v135, v134
	v_cndmask_b32_e32 v135, v134, v135, vcc
	v_mul_f32_e32 v134, v139, v142
	v_cndmask_b32_e32 v139, v142, v134, vcc
	v_cvt_pk_bf16_f32 v134, v0, v137
	v_cvt_pk_bf16_f32 v135, v141, v135
	v_cvt_pk_bf16_f32 v136, v136, v140
	v_cvt_pk_bf16_f32 v137, v138, v139
	global_store_dwordx4 v[132:133], v[134:137], off offset:64
	s_nop 1
	v_add_u32_e32 v134, 0x80, v170
	v_ashrrev_i32_e32 v135, 31, v134
	v_lshlrev_b64 v[132:133], 11, v[134:135]
	v_lshl_add_u64 v[132:133], v[130:131], 0, v[132:133]
	s_waitcnt vmcnt(2)
	v_pk_add_f32 v[136:137], v[192:193], v[196:197]
	v_pk_add_f32 v[134:135], v[190:191], v[194:195]
	v_pk_add_f32 v[144:145], v[200:201], v[204:205]
	v_pk_add_f32 v[142:143], v[198:199], v[202:203]
	v_pk_add_f32 v[136:137], v[144:145], v[136:137]
	v_pk_add_f32 v[134:135], v[142:143], v[134:135]
	s_nop 0
	v_pk_mov_b32 v[138:139], v[134:135], v[136:137] op_sel:[1,0]
	v_mov_b32_e32 v135, v137
	v_pk_add_f32 v[134:135], v[138:139], v[134:135]
	s_nop 0
	v_add_f32_e32 v0, v134, v135
	v_fmamk_f32 v0, v0, 0x3a800000, v211
	v_rsq_f32_e32 v0, v0
	s_nop 0
	v_add_u32_e32 v186, 0x90, v170
	v_ashrrev_i32_e32 v187, 31, v186
	v_lshlrev_b64 v[188:189], 6, v[186:187]
	v_lshl_add_u64 v[188:189], s[92:93], 0, v[188:189]
	global_load_dwordx4 v[190:193], v[188:189], off offset:32
	global_load_dwordx4 v[194:197], v[188:189], off offset:48
	global_load_dwordx4 v[198:201], v[188:189], off
	global_load_dwordx4 v[202:205], v[188:189], off offset:16
	v_pk_mul_f32 v[136:137], v[62:63], v[0:1] op_sel_hi:[1,0]
	v_pk_mul_f32 v[140:141], v[58:59], v[0:1] op_sel_hi:[1,0]
	v_mul_f32_e32 v142, 0xbfb8aa3b, v136
	v_exp_f32_e32 v142, v142
	v_mul_f32_e32 v143, 0xbfb8aa3b, v140
	v_exp_f32_e32 v143, v143
	v_pk_mul_f32 v[134:135], v[64:65], v[0:1] op_sel_hi:[1,0]
	v_add_f32_e32 v142, 1.0, v142
	v_rcp_f32_e32 v142, v142
	v_add_f32_e32 v143, 1.0, v143
	v_rcp_f32_e32 v143, v143
	v_pk_mul_f32 v[138:139], v[60:61], v[0:1] op_sel_hi:[1,0]
	v_mul_f32_e32 v136, v136, v142
	v_cndmask_b32_e32 v136, v142, v136, vcc
	v_mul_f32_e32 v140, v140, v143
	v_mul_f32_e32 v142, 0xbfb8aa3b, v137
	v_cndmask_b32_e32 v140, v143, v140, vcc
	v_exp_f32_e32 v142, v142
	v_mul_f32_e32 v143, 0xbfb8aa3b, v141
	v_exp_f32_e32 v143, v143
	v_add_f32_e32 v142, 1.0, v142
	v_rcp_f32_e32 v142, v142
	v_add_f32_e32 v143, 1.0, v143
	v_rcp_f32_e32 v143, v143
	v_mul_f32_e32 v137, v137, v142
	v_cndmask_b32_e32 v137, v142, v137, vcc
	v_mul_f32_e32 v141, v141, v143
	v_mul_f32_e32 v142, 0xbfb8aa3b, v134
	v_cndmask_b32_e32 v141, v143, v141, vcc
	v_exp_f32_e32 v142, v142
	v_mul_f32_e32 v143, 0xbfb8aa3b, v138
	v_exp_f32_e32 v143, v143
	v_add_f32_e32 v142, 1.0, v142
	v_rcp_f32_e32 v142, v142
	v_add_f32_e32 v143, 1.0, v143
	v_rcp_f32_e32 v143, v143
	v_mul_f32_e32 v134, v134, v142
	v_cndmask_b32_e32 v142, v142, v134, vcc
	v_mul_f32_e32 v134, v138, v143
	v_cndmask_b32_e32 v138, v143, v134, vcc
	v_mul_f32_e32 v134, 0xbfb8aa3b, v135
	v_exp_f32_e32 v134, v134
	v_mul_f32_e32 v143, 0xbfb8aa3b, v139
	v_exp_f32_e32 v143, v143
	v_add_f32_e32 v134, 1.0, v134
	v_rcp_f32_e32 v134, v134
	v_add_f32_e32 v143, 1.0, v143
	v_rcp_f32_e32 v143, v143
	v_mul_f32_e32 v135, v135, v134
	v_cndmask_b32_e32 v135, v134, v135, vcc
	v_mul_f32_e32 v134, v139, v143
	v_cndmask_b32_e32 v139, v143, v134, vcc
	v_cvt_pk_bf16_f32 v134, v136, v137
	v_cvt_pk_bf16_f32 v135, v142, v135
	v_cvt_pk_bf16_f32 v136, v140, v141
	v_cvt_pk_bf16_f32 v137, v138, v139
	global_store_dwordx4 v[132:133], v[134:137], off
	v_pk_mul_f32 v[138:139], v[48:49], v[0:1] op_sel_hi:[1,0]
	v_pk_mul_f32 v[140:141], v[46:47], v[0:1] op_sel_hi:[1,0]
	v_pk_mul_f32 v[136:137], v[54:55], v[0:1] op_sel_hi:[1,0]
	v_pk_mul_f32 v[134:135], v[56:57], v[0:1] op_sel_hi:[1,0]
	v_mul_f32_e32 v0, 0xbfb8aa3b, v136
	v_exp_f32_e32 v0, v0
	v_mul_f32_e32 v142, 0xbfb8aa3b, v140
	v_exp_f32_e32 v142, v142
	v_add_f32_e32 v0, 1.0, v0
	v_rcp_f32_e32 v0, v0
	v_add_f32_e32 v142, 1.0, v142
	v_rcp_f32_e32 v142, v142
	v_mul_f32_e32 v136, v136, v0
	v_cndmask_b32_e32 v0, v0, v136, vcc
	v_mul_f32_e32 v136, v140, v142
	v_mul_f32_e32 v140, 0xbfb8aa3b, v137
	v_cndmask_b32_e32 v136, v142, v136, vcc
	v_exp_f32_e32 v140, v140
	v_mul_f32_e32 v142, 0xbfb8aa3b, v141
	v_exp_f32_e32 v142, v142
	v_add_f32_e32 v140, 1.0, v140
	v_rcp_f32_e32 v140, v140
	v_add_f32_e32 v142, 1.0, v142
	v_rcp_f32_e32 v142, v142
	v_mul_f32_e32 v137, v137, v140
	v_cndmask_b32_e32 v137, v140, v137, vcc
	v_mul_f32_e32 v140, v141, v142
	v_mul_f32_e32 v141, 0xbfb8aa3b, v134
	v_cndmask_b32_e32 v140, v142, v140, vcc
	v_exp_f32_e32 v141, v141
	v_mul_f32_e32 v142, 0xbfb8aa3b, v138
	v_exp_f32_e32 v142, v142
	v_add_f32_e32 v141, 1.0, v141
	v_rcp_f32_e32 v141, v141
	v_add_f32_e32 v142, 1.0, v142
	v_rcp_f32_e32 v142, v142
	v_mul_f32_e32 v134, v134, v141
	v_cndmask_b32_e32 v141, v141, v134, vcc
	v_mul_f32_e32 v134, v138, v142
	v_cndmask_b32_e32 v138, v142, v134, vcc
	v_mul_f32_e32 v134, 0xbfb8aa3b, v135
	v_exp_f32_e32 v134, v134
	v_mul_f32_e32 v142, 0xbfb8aa3b, v139
	v_exp_f32_e32 v142, v142
	v_add_f32_e32 v134, 1.0, v134
	v_rcp_f32_e32 v134, v134
	v_add_f32_e32 v142, 1.0, v142
	v_rcp_f32_e32 v142, v142
	v_mul_f32_e32 v135, v135, v134
	v_cndmask_b32_e32 v135, v134, v135, vcc
	v_mul_f32_e32 v134, v139, v142
	v_cndmask_b32_e32 v139, v142, v134, vcc
	v_cvt_pk_bf16_f32 v134, v0, v137
	v_cvt_pk_bf16_f32 v135, v141, v135
	v_cvt_pk_bf16_f32 v136, v136, v140
	v_cvt_pk_bf16_f32 v137, v138, v139
	global_store_dwordx4 v[132:133], v[134:137], off offset:64
	s_nop 1
	v_add_u32_e32 v134, 0x90, v170
	v_ashrrev_i32_e32 v135, 31, v134
	v_lshlrev_b64 v[132:133], 11, v[134:135]
	v_lshl_add_u64 v[132:133], v[130:131], 0, v[132:133]
	s_waitcnt vmcnt(2)
	v_pk_add_f32 v[136:137], v[192:193], v[196:197]
	v_pk_add_f32 v[134:135], v[190:191], v[194:195]
	v_pk_add_f32 v[144:145], v[200:201], v[204:205]
	v_pk_add_f32 v[142:143], v[198:199], v[202:203]
	v_pk_add_f32 v[136:137], v[144:145], v[136:137]
	v_pk_add_f32 v[134:135], v[142:143], v[134:135]
	s_nop 0
	v_pk_mov_b32 v[138:139], v[134:135], v[136:137] op_sel:[1,0]
	v_mov_b32_e32 v135, v137
	v_pk_add_f32 v[134:135], v[138:139], v[134:135]
	s_nop 0
	v_add_f32_e32 v0, v134, v135
	v_fmamk_f32 v0, v0, 0x3a800000, v211
	v_rsq_f32_e32 v0, v0
	s_nop 0
	v_add_u32_e32 v186, 0xa0, v170
	v_ashrrev_i32_e32 v187, 31, v186
	v_lshlrev_b64 v[188:189], 6, v[186:187]
	v_lshl_add_u64 v[188:189], s[92:93], 0, v[188:189]
	global_load_dwordx4 v[190:193], v[188:189], off offset:32
	global_load_dwordx4 v[194:197], v[188:189], off offset:48
	global_load_dwordx4 v[198:201], v[188:189], off
	global_load_dwordx4 v[202:205], v[188:189], off offset:16
	v_pk_mul_f32 v[136:137], v[50:51], v[0:1] op_sel_hi:[1,0]
	v_pk_mul_f32 v[140:141], v[42:43], v[0:1] op_sel_hi:[1,0]
	v_mul_f32_e32 v142, 0xbfb8aa3b, v136
	v_exp_f32_e32 v142, v142
	v_mul_f32_e32 v143, 0xbfb8aa3b, v140
	v_exp_f32_e32 v143, v143
	v_pk_mul_f32 v[134:135], v[52:53], v[0:1] op_sel_hi:[1,0]
	v_add_f32_e32 v142, 1.0, v142
	v_rcp_f32_e32 v142, v142
	v_add_f32_e32 v143, 1.0, v143
	v_rcp_f32_e32 v143, v143
	v_pk_mul_f32 v[138:139], v[44:45], v[0:1] op_sel_hi:[1,0]
	v_mul_f32_e32 v136, v136, v142
	v_cndmask_b32_e32 v136, v142, v136, vcc
	v_mul_f32_e32 v140, v140, v143
	v_mul_f32_e32 v142, 0xbfb8aa3b, v137
	v_cndmask_b32_e32 v140, v143, v140, vcc
	v_exp_f32_e32 v142, v142
	v_mul_f32_e32 v143, 0xbfb8aa3b, v141
	v_exp_f32_e32 v143, v143
	v_add_f32_e32 v142, 1.0, v142
	v_rcp_f32_e32 v142, v142
	v_add_f32_e32 v143, 1.0, v143
	v_rcp_f32_e32 v143, v143
	v_mul_f32_e32 v137, v137, v142
	v_cndmask_b32_e32 v137, v142, v137, vcc
	v_mul_f32_e32 v141, v141, v143
	v_mul_f32_e32 v142, 0xbfb8aa3b, v134
	v_cndmask_b32_e32 v141, v143, v141, vcc
	v_exp_f32_e32 v142, v142
	v_mul_f32_e32 v143, 0xbfb8aa3b, v138
	v_exp_f32_e32 v143, v143
	v_add_f32_e32 v142, 1.0, v142
	v_rcp_f32_e32 v142, v142
	v_add_f32_e32 v143, 1.0, v143
	v_rcp_f32_e32 v143, v143
	v_mul_f32_e32 v134, v134, v142
	v_cndmask_b32_e32 v142, v142, v134, vcc
	v_mul_f32_e32 v134, v138, v143
	v_cndmask_b32_e32 v138, v143, v134, vcc
	v_mul_f32_e32 v134, 0xbfb8aa3b, v135
	v_exp_f32_e32 v134, v134
	v_mul_f32_e32 v143, 0xbfb8aa3b, v139
	v_exp_f32_e32 v143, v143
	v_add_f32_e32 v134, 1.0, v134
	v_rcp_f32_e32 v134, v134
	v_add_f32_e32 v143, 1.0, v143
	v_rcp_f32_e32 v143, v143
	v_mul_f32_e32 v135, v135, v134
	v_cndmask_b32_e32 v135, v134, v135, vcc
	v_mul_f32_e32 v134, v139, v143
	v_cndmask_b32_e32 v139, v143, v134, vcc
	v_cvt_pk_bf16_f32 v134, v136, v137
	v_cvt_pk_bf16_f32 v135, v142, v135
	v_cvt_pk_bf16_f32 v136, v140, v141
	v_cvt_pk_bf16_f32 v137, v138, v139
	global_store_dwordx4 v[132:133], v[134:137], off
	v_pk_mul_f32 v[138:139], v[32:33], v[0:1] op_sel_hi:[1,0]
	v_pk_mul_f32 v[140:141], v[30:31], v[0:1] op_sel_hi:[1,0]
	v_pk_mul_f32 v[136:137], v[38:39], v[0:1] op_sel_hi:[1,0]
	v_pk_mul_f32 v[134:135], v[40:41], v[0:1] op_sel_hi:[1,0]
	v_mul_f32_e32 v0, 0xbfb8aa3b, v136
	v_exp_f32_e32 v0, v0
	v_mul_f32_e32 v142, 0xbfb8aa3b, v140
	v_exp_f32_e32 v142, v142
	v_add_f32_e32 v0, 1.0, v0
	v_rcp_f32_e32 v0, v0
	v_add_f32_e32 v142, 1.0, v142
	v_rcp_f32_e32 v142, v142
	v_mul_f32_e32 v136, v136, v0
	v_cndmask_b32_e32 v0, v0, v136, vcc
	v_mul_f32_e32 v136, v140, v142
	v_mul_f32_e32 v140, 0xbfb8aa3b, v137
	v_cndmask_b32_e32 v136, v142, v136, vcc
	v_exp_f32_e32 v140, v140
	v_mul_f32_e32 v142, 0xbfb8aa3b, v141
	v_exp_f32_e32 v142, v142
	v_add_f32_e32 v140, 1.0, v140
	v_rcp_f32_e32 v140, v140
	v_add_f32_e32 v142, 1.0, v142
	v_rcp_f32_e32 v142, v142
	v_mul_f32_e32 v137, v137, v140
	v_cndmask_b32_e32 v137, v140, v137, vcc
	v_mul_f32_e32 v140, v141, v142
	v_mul_f32_e32 v141, 0xbfb8aa3b, v134
	v_cndmask_b32_e32 v140, v142, v140, vcc
	v_exp_f32_e32 v141, v141
	v_mul_f32_e32 v142, 0xbfb8aa3b, v138
	v_exp_f32_e32 v142, v142
	v_add_f32_e32 v141, 1.0, v141
	v_rcp_f32_e32 v141, v141
	v_add_f32_e32 v142, 1.0, v142
	v_rcp_f32_e32 v142, v142
	v_mul_f32_e32 v134, v134, v141
	v_cndmask_b32_e32 v141, v141, v134, vcc
	v_mul_f32_e32 v134, v138, v142
	v_cndmask_b32_e32 v138, v142, v134, vcc
	v_mul_f32_e32 v134, 0xbfb8aa3b, v135
	v_exp_f32_e32 v134, v134
	v_mul_f32_e32 v142, 0xbfb8aa3b, v139
	v_exp_f32_e32 v142, v142
	v_add_f32_e32 v134, 1.0, v134
	v_rcp_f32_e32 v134, v134
	v_add_f32_e32 v142, 1.0, v142
	v_rcp_f32_e32 v142, v142
	v_mul_f32_e32 v135, v135, v134
	v_cndmask_b32_e32 v135, v134, v135, vcc
	v_mul_f32_e32 v134, v139, v142
	v_cndmask_b32_e32 v139, v142, v134, vcc
	v_cvt_pk_bf16_f32 v134, v0, v137
	v_cvt_pk_bf16_f32 v135, v141, v135
	v_cvt_pk_bf16_f32 v136, v136, v140
	v_cvt_pk_bf16_f32 v137, v138, v139
	global_store_dwordx4 v[132:133], v[134:137], off offset:64
	s_nop 1
	v_add_u32_e32 v134, 0xa0, v170
	v_ashrrev_i32_e32 v135, 31, v134
	v_lshlrev_b64 v[132:133], 11, v[134:135]
	v_lshl_add_u64 v[132:133], v[130:131], 0, v[132:133]
	s_waitcnt vmcnt(2)
	v_pk_add_f32 v[136:137], v[192:193], v[196:197]
	v_pk_add_f32 v[134:135], v[190:191], v[194:195]
	v_pk_add_f32 v[144:145], v[200:201], v[204:205]
	v_pk_add_f32 v[142:143], v[198:199], v[202:203]
	v_pk_add_f32 v[136:137], v[144:145], v[136:137]
	v_pk_add_f32 v[134:135], v[142:143], v[134:135]
	s_nop 0
	v_pk_mov_b32 v[138:139], v[134:135], v[136:137] op_sel:[1,0]
	v_mov_b32_e32 v135, v137
	v_pk_add_f32 v[134:135], v[138:139], v[134:135]
	s_nop 0
	v_add_f32_e32 v0, v134, v135
	v_fmamk_f32 v0, v0, 0x3a800000, v211
	v_rsq_f32_e32 v0, v0
	s_nop 0
	v_pk_mul_f32 v[136:137], v[34:35], v[0:1] op_sel_hi:[1,0]
	v_pk_mul_f32 v[140:141], v[26:27], v[0:1] op_sel_hi:[1,0]
	v_mul_f32_e32 v142, 0xbfb8aa3b, v136
	v_exp_f32_e32 v142, v142
	v_mul_f32_e32 v143, 0xbfb8aa3b, v140
	v_exp_f32_e32 v143, v143
	v_pk_mul_f32 v[134:135], v[36:37], v[0:1] op_sel_hi:[1,0]
	v_add_f32_e32 v142, 1.0, v142
	v_rcp_f32_e32 v142, v142
	v_add_f32_e32 v143, 1.0, v143
	v_rcp_f32_e32 v143, v143
	v_pk_mul_f32 v[138:139], v[28:29], v[0:1] op_sel_hi:[1,0]
	v_mul_f32_e32 v136, v136, v142
	v_cndmask_b32_e32 v136, v142, v136, vcc
	v_mul_f32_e32 v140, v140, v143
	v_mul_f32_e32 v142, 0xbfb8aa3b, v137
	v_cndmask_b32_e32 v140, v143, v140, vcc
	v_exp_f32_e32 v142, v142
	v_mul_f32_e32 v143, 0xbfb8aa3b, v141
	v_exp_f32_e32 v143, v143
	v_add_f32_e32 v142, 1.0, v142
	v_rcp_f32_e32 v142, v142
	v_add_f32_e32 v143, 1.0, v143
	v_rcp_f32_e32 v143, v143
	v_mul_f32_e32 v137, v137, v142
	v_cndmask_b32_e32 v137, v142, v137, vcc
	v_mul_f32_e32 v141, v141, v143
	v_mul_f32_e32 v142, 0xbfb8aa3b, v134
	v_cndmask_b32_e32 v141, v143, v141, vcc
	v_exp_f32_e32 v142, v142
	v_mul_f32_e32 v143, 0xbfb8aa3b, v138
	v_exp_f32_e32 v143, v143
	v_add_f32_e32 v142, 1.0, v142
	v_rcp_f32_e32 v142, v142
	v_add_f32_e32 v143, 1.0, v143
	v_rcp_f32_e32 v143, v143
	v_mul_f32_e32 v134, v134, v142
	v_cndmask_b32_e32 v142, v142, v134, vcc
	v_mul_f32_e32 v134, v138, v143
	v_cndmask_b32_e32 v138, v143, v134, vcc
	v_mul_f32_e32 v134, 0xbfb8aa3b, v135
	v_exp_f32_e32 v134, v134
	v_mul_f32_e32 v143, 0xbfb8aa3b, v139
	v_exp_f32_e32 v143, v143
	v_add_f32_e32 v134, 1.0, v134
	v_rcp_f32_e32 v134, v134
	v_add_f32_e32 v143, 1.0, v143
	v_rcp_f32_e32 v143, v143
	v_mul_f32_e32 v135, v135, v134
	v_cndmask_b32_e32 v135, v134, v135, vcc
	v_mul_f32_e32 v134, v139, v143
	v_cndmask_b32_e32 v139, v143, v134, vcc
	v_cvt_pk_bf16_f32 v134, v136, v137
	v_cvt_pk_bf16_f32 v135, v142, v135
	v_cvt_pk_bf16_f32 v136, v140, v141
	v_cvt_pk_bf16_f32 v137, v138, v139
	global_store_dwordx4 v[132:133], v[134:137], off
	v_pk_mul_f32 v[138:139], v[16:17], v[0:1] op_sel_hi:[1,0]
	v_pk_mul_f32 v[140:141], v[14:15], v[0:1] op_sel_hi:[1,0]
	v_pk_mul_f32 v[136:137], v[22:23], v[0:1] op_sel_hi:[1,0]
	v_pk_mul_f32 v[134:135], v[24:25], v[0:1] op_sel_hi:[1,0]
	v_mul_f32_e32 v0, 0xbfb8aa3b, v136
	v_exp_f32_e32 v0, v0
	v_mul_f32_e32 v142, 0xbfb8aa3b, v140
	v_exp_f32_e32 v142, v142
	v_add_f32_e32 v0, 1.0, v0
	v_rcp_f32_e32 v0, v0
	v_add_f32_e32 v142, 1.0, v142
	v_rcp_f32_e32 v142, v142
	v_mul_f32_e32 v136, v136, v0
	v_cndmask_b32_e32 v0, v0, v136, vcc
	v_mul_f32_e32 v136, v140, v142
	v_mul_f32_e32 v140, 0xbfb8aa3b, v137
	v_cndmask_b32_e32 v136, v142, v136, vcc
	v_exp_f32_e32 v140, v140
	v_mul_f32_e32 v142, 0xbfb8aa3b, v141
	v_exp_f32_e32 v142, v142
	v_add_f32_e32 v140, 1.0, v140
	v_rcp_f32_e32 v140, v140
	v_add_f32_e32 v142, 1.0, v142
	v_rcp_f32_e32 v142, v142
	v_mul_f32_e32 v137, v137, v140
	v_cndmask_b32_e32 v137, v140, v137, vcc
	v_mul_f32_e32 v140, v141, v142
	v_mul_f32_e32 v141, 0xbfb8aa3b, v134
	v_cndmask_b32_e32 v140, v142, v140, vcc
	v_exp_f32_e32 v141, v141
	v_mul_f32_e32 v142, 0xbfb8aa3b, v138
	v_exp_f32_e32 v142, v142
	v_add_f32_e32 v141, 1.0, v141
	v_rcp_f32_e32 v141, v141
	v_add_f32_e32 v142, 1.0, v142
	v_rcp_f32_e32 v142, v142
	v_mul_f32_e32 v134, v134, v141
	v_cndmask_b32_e32 v141, v141, v134, vcc
	v_mul_f32_e32 v134, v138, v142
	v_cndmask_b32_e32 v138, v142, v134, vcc
	v_mul_f32_e32 v134, 0xbfb8aa3b, v135
	v_exp_f32_e32 v134, v134
	v_mul_f32_e32 v142, 0xbfb8aa3b, v139
	v_exp_f32_e32 v142, v142
	v_add_f32_e32 v134, 1.0, v134
	v_rcp_f32_e32 v134, v134
	v_add_f32_e32 v142, 1.0, v142
	v_rcp_f32_e32 v142, v142
	v_mul_f32_e32 v135, v135, v134
	v_cndmask_b32_e32 v135, v134, v135, vcc
	v_mul_f32_e32 v134, v139, v142
	v_cndmask_b32_e32 v139, v142, v134, vcc
	v_cvt_pk_bf16_f32 v134, v0, v137
	v_cvt_pk_bf16_f32 v135, v141, v135
	v_cvt_pk_bf16_f32 v136, v136, v140
	v_cvt_pk_bf16_f32 v137, v138, v139
	global_store_dwordx4 v[132:133], v[134:137], off offset:64
	v_add_u32_e32 v132, 0xb0, v170
	v_ashrrev_i32_e32 v133, 31, v132
	v_lshlrev_b64 v[134:135], 11, v[132:133]
	v_lshlrev_b64 v[132:133], 6, v[132:133]
	v_lshl_add_u64 v[144:145], s[92:93], 0, v[132:133]
	v_lshl_add_u64 v[130:131], v[130:131], 0, v[134:135]
	global_load_dwordx4 v[132:135], v[144:145], off offset:32
	global_load_dwordx4 v[136:139], v[144:145], off offset:48
	global_load_dwordx4 v[140:143], v[144:145], off
	s_nop 0
	global_load_dwordx4 v[144:147], v[144:145], off offset:16
	s_waitcnt vmcnt(2)
	v_pk_add_f32 v[134:135], v[134:135], v[138:139]
	v_pk_add_f32 v[132:133], v[132:133], v[136:137]
	s_waitcnt vmcnt(0)
	v_pk_add_f32 v[142:143], v[142:143], v[146:147]
	v_pk_add_f32 v[140:141], v[140:141], v[144:145]
	v_pk_add_f32 v[134:135], v[142:143], v[134:135]
	v_pk_add_f32 v[132:133], v[140:141], v[132:133]
	s_nop 0
	v_pk_mov_b32 v[136:137], v[132:133], v[134:135] op_sel:[1,0]
	v_mov_b32_e32 v133, v135
	v_pk_add_f32 v[132:133], v[136:137], v[132:133]
	s_nop 0
	v_add_f32_e32 v0, v132, v133
	v_fmamk_f32 v0, v0, 0x3a800000, v211
	v_rsq_f32_e32 v0, v0
	s_nop 0
	v_pk_mul_f32 v[134:135], v[18:19], v[0:1] op_sel_hi:[1,0]
	v_pk_mul_f32 v[138:139], v[10:11], v[0:1] op_sel_hi:[1,0]
	v_mul_f32_e32 v140, 0xbfb8aa3b, v134
	v_exp_f32_e32 v140, v140
	v_mul_f32_e32 v141, 0xbfb8aa3b, v138
	v_exp_f32_e32 v141, v141
	v_pk_mul_f32 v[132:133], v[20:21], v[0:1] op_sel_hi:[1,0]
	v_add_f32_e32 v140, 1.0, v140
	v_rcp_f32_e32 v140, v140
	v_add_f32_e32 v141, 1.0, v141
	v_rcp_f32_e32 v141, v141
	v_pk_mul_f32 v[136:137], v[12:13], v[0:1] op_sel_hi:[1,0]
	v_mul_f32_e32 v134, v134, v140
	v_cndmask_b32_e32 v134, v140, v134, vcc
	v_mul_f32_e32 v138, v138, v141
	v_mul_f32_e32 v140, 0xbfb8aa3b, v135
	v_cndmask_b32_e32 v138, v141, v138, vcc
	v_exp_f32_e32 v140, v140
	v_mul_f32_e32 v141, 0xbfb8aa3b, v139
	v_exp_f32_e32 v141, v141
	v_add_f32_e32 v140, 1.0, v140
	v_rcp_f32_e32 v140, v140
	v_add_f32_e32 v141, 1.0, v141
	v_rcp_f32_e32 v141, v141
	v_mul_f32_e32 v135, v135, v140
	v_cndmask_b32_e32 v135, v140, v135, vcc
	v_mul_f32_e32 v139, v139, v141
	v_mul_f32_e32 v140, 0xbfb8aa3b, v132
	v_cndmask_b32_e32 v139, v141, v139, vcc
	v_exp_f32_e32 v140, v140
	v_mul_f32_e32 v141, 0xbfb8aa3b, v136
	v_exp_f32_e32 v141, v141
	v_add_f32_e32 v140, 1.0, v140
	v_rcp_f32_e32 v140, v140
	v_add_f32_e32 v141, 1.0, v141
	v_rcp_f32_e32 v141, v141
	v_mul_f32_e32 v132, v132, v140
	v_cndmask_b32_e32 v140, v140, v132, vcc
	v_mul_f32_e32 v132, v136, v141
	v_cndmask_b32_e32 v136, v141, v132, vcc
	v_mul_f32_e32 v132, 0xbfb8aa3b, v133
	v_exp_f32_e32 v132, v132
	v_mul_f32_e32 v141, 0xbfb8aa3b, v137
	v_exp_f32_e32 v141, v141
	v_add_f32_e32 v132, 1.0, v132
	v_rcp_f32_e32 v132, v132
	v_add_f32_e32 v141, 1.0, v141
	v_rcp_f32_e32 v141, v141
	v_mul_f32_e32 v133, v133, v132
	v_cndmask_b32_e32 v133, v132, v133, vcc
	v_mul_f32_e32 v132, v137, v141
	v_cndmask_b32_e32 v137, v141, v132, vcc
	v_cvt_pk_bf16_f32 v132, v134, v135
	v_cvt_pk_bf16_f32 v133, v140, v133
	v_cvt_pk_bf16_f32 v134, v138, v139
	v_cvt_pk_bf16_f32 v135, v136, v137
	global_store_dwordx4 v[130:131], v[132:135], off
	v_pk_mul_f32 v[136:137], v[4:5], v[0:1] op_sel_hi:[1,0]
	v_pk_mul_f32 v[138:139], v[2:3], v[0:1] op_sel_hi:[1,0]
	v_pk_mul_f32 v[134:135], v[6:7], v[0:1] op_sel_hi:[1,0]
	v_pk_mul_f32 v[132:133], v[8:9], v[0:1] op_sel_hi:[1,0]
	v_mul_f32_e32 v0, 0xbfb8aa3b, v134
	v_exp_f32_e32 v0, v0
	v_mul_f32_e32 v140, 0xbfb8aa3b, v138
	v_exp_f32_e32 v140, v140
	v_add_f32_e32 v0, 1.0, v0
	v_rcp_f32_e32 v0, v0
	v_add_f32_e32 v140, 1.0, v140
	v_rcp_f32_e32 v140, v140
	v_mul_f32_e32 v134, v134, v0
	v_cndmask_b32_e32 v0, v0, v134, vcc
	v_mul_f32_e32 v134, v138, v140
	v_mul_f32_e32 v138, 0xbfb8aa3b, v135
	v_cndmask_b32_e32 v134, v140, v134, vcc
	v_exp_f32_e32 v138, v138
	v_mul_f32_e32 v140, 0xbfb8aa3b, v139
	v_exp_f32_e32 v140, v140
	v_add_f32_e32 v138, 1.0, v138
	v_rcp_f32_e32 v138, v138
	v_add_f32_e32 v140, 1.0, v140
	v_rcp_f32_e32 v140, v140
	v_mul_f32_e32 v135, v135, v138
	v_cndmask_b32_e32 v135, v138, v135, vcc
	v_mul_f32_e32 v138, v139, v140
	v_mul_f32_e32 v139, 0xbfb8aa3b, v132
	v_cndmask_b32_e32 v138, v140, v138, vcc
	v_exp_f32_e32 v139, v139
	v_mul_f32_e32 v140, 0xbfb8aa3b, v136
	v_exp_f32_e32 v140, v140
	v_add_f32_e32 v139, 1.0, v139
	v_rcp_f32_e32 v139, v139
	v_add_f32_e32 v140, 1.0, v140
	v_rcp_f32_e32 v140, v140
	v_mul_f32_e32 v132, v132, v139
	v_cndmask_b32_e32 v139, v139, v132, vcc
	v_mul_f32_e32 v132, v136, v140
	v_cndmask_b32_e32 v136, v140, v132, vcc
	v_mul_f32_e32 v132, 0xbfb8aa3b, v133
	v_exp_f32_e32 v132, v132
	v_mul_f32_e32 v140, 0xbfb8aa3b, v137
	v_exp_f32_e32 v140, v140
	v_add_f32_e32 v132, 1.0, v132
	v_rcp_f32_e32 v132, v132
	v_add_f32_e32 v140, 1.0, v140
	v_rcp_f32_e32 v140, v140
	v_mul_f32_e32 v133, v133, v132
	v_cndmask_b32_e32 v133, v132, v133, vcc
	v_mul_f32_e32 v132, v137, v140
	v_cndmask_b32_e32 v137, v140, v132, vcc
	v_cvt_pk_bf16_f32 v132, v0, v135
	v_cvt_pk_bf16_f32 v133, v139, v133
	v_cvt_pk_bf16_f32 v134, v134, v138
	v_cvt_pk_bf16_f32 v135, v136, v137
	global_store_dwordx4 v[130:131], v[132:135], off offset:64
